# v015 + PV block of the diff-attention step reordered: the eight MFMAs whose V fragments were read before the softmax issue first, giving the second V read batch time to land
# baseline (speedup 1.0000x reference)
; __device__ __forceinline__ float fast_exp2(float x) { return __builtin_amdgcn_exp2f(x); }
; #define MFMA32(a, b, c) __builtin_amdgcn_mfma_f32_32x32x16_bf16((a), (b), (c), 0, 0, 0)
; template <bool DIFF, int NDV>
; __device__ __forceinline__ void attn_tile(f32x16 (&o)[NDV], float& l, const bf16x8 (&qf)[4], const float sref, LAS const char* kc, LAS const char* vc,
;                                           bool masked, int kb0, int qrow) {
;     ...
;     float rs = 0.f;
; #pragma unroll
;     for (int i = 0; i < 16; ++i) { s0[i] = fast_exp2(s0[i]); s1[i] = fast_exp2(s1[i]); rs += s0[i] + s1[i]; }
;     l += rs;
;     bf16x8 pb[4];
;     pb[0] = pack8(s0, 0); pb[1] = pack8(s0, 1); pb[2] = pack8(s1, 0); pb[3] = pack8(s1, 1);
;     if (NDV == 4) {
;         bf16x8 vf2[8];
; #pragma unroll
;         for (int d = 0; d < 2; ++d)
; #pragma unroll
;             for (int kk = 0; kk < 4; ++kk) vf2[d * 4 + kk] = vtr8(vc + kk * 16 * ATT_VP + (d + 2) * 64, 8 * ATT_VP);
;         __builtin_amdgcn_sched_barrier(0);
; #pragma unroll
;         for (int kk = 0; kk < 4; ++kk) { o[0] = MFMA32(vf[kk], pb[kk], o[0]); o[1] = MFMA32(vf[4 + kk], pb[kk], o[1]); }
; #pragma unroll
;         for (int kk = 0; kk < 4; ++kk) { o[2] = MFMA32(vf2[kk], pb[kk], o[2]); o[NDV - 1] = MFMA32(vf2[4 + kk], pb[kk], o[NDV - 1]); }
.LBB0_48:
	s_waitcnt vmcnt(6)
	ds_write_b128 v230, v[128:131] offset:17408
	s_waitcnt vmcnt(5)
	ds_write_b128 v230, v[136:139] offset:17424
	s_waitcnt vmcnt(4)
	ds_write_b128 v228, v[132:135] offset:55296
	s_waitcnt vmcnt(4)
	ds_write_b128 v228, v[140:143] offset:55312
	v_exp_f32_e32 v199, v96
	s_nop 7
	v_exp_f32_e32 v236, v80
	v_exp_f32_e32 v0, v97
	v_exp_f32_e32 v206, v81
	v_exp_f32_e32 v237, v82
	v_add_f32_e32 v207, v236, v199
	v_exp_f32_e32 v234, v83
	v_pk_add_f32 v[80:81], v[206:207], v[0:1]
	v_exp_f32_e32 v207, v98
	v_pk_add_f32 v[96:97], v[80:81], v[80:81] op_sel_hi:[0,1]
	v_exp_f32_e32 v96, v99
	v_exp_f32_e32 v98, v85
	v_add_f32_e32 v235, v237, v207
	v_pk_add_f32 v[80:81], v[234:235], v[96:97]
	s_nop 0
	v_pk_add_f32 v[82:83], v[80:81], v[80:81] op_sel_hi:[0,1]
	v_exp_f32_e32 v97, v100
	v_exp_f32_e32 v235, v84
	v_exp_f32_e32 v82, v101
	v_exp_f32_e32 v100, v87
	v_add_f32_e32 v99, v235, v97
	v_pk_add_f32 v[80:81], v[98:99], v[82:83]
	v_exp_f32_e32 v83, v102
	v_pk_add_f32 v[84:85], v[80:81], v[80:81] op_sel_hi:[0,1]
	v_exp_f32_e32 v99, v86
	v_exp_f32_e32 v84, v103
	v_exp_f32_e32 v102, v89
	v_cvt_pk_bf16_f32 v82, v97, v82
	v_add_f32_e32 v101, v99, v83
	v_pk_add_f32 v[80:81], v[100:101], v[84:85]
	v_exp_f32_e32 v85, v104
	v_pk_add_f32 v[86:87], v[80:81], v[80:81] op_sel_hi:[0,1]
	v_exp_f32_e32 v101, v88
	v_exp_f32_e32 v86, v105
	v_exp_f32_e32 v104, v91
	v_cvt_pk_bf16_f32 v83, v83, v84
	v_add_f32_e32 v103, v101, v85
	v_pk_add_f32 v[80:81], v[102:103], v[86:87]
	v_exp_f32_e32 v87, v106
	v_pk_add_f32 v[88:89], v[80:81], v[80:81] op_sel_hi:[0,1]
	v_exp_f32_e32 v103, v90
	v_exp_f32_e32 v88, v107
	v_exp_f32_e32 v106, v93
	v_cvt_pk_bf16_f32 v84, v85, v86
	v_add_f32_e32 v105, v103, v87
	v_pk_add_f32 v[80:81], v[104:105], v[88:89]
	v_exp_f32_e32 v89, v108
	v_pk_add_f32 v[90:91], v[80:81], v[80:81] op_sel_hi:[0,1]
	v_exp_f32_e32 v105, v92
	v_exp_f32_e32 v90, v109
	v_exp_f32_e32 v108, v95
	v_cvt_pk_bf16_f32 v85, v87, v88
	v_add_f32_e32 v107, v105, v89
	v_pk_add_f32 v[80:81], v[106:107], v[90:91]
	v_exp_f32_e32 v91, v110
	v_pk_add_f32 v[92:93], v[80:81], v[80:81] op_sel_hi:[0,1]
	v_exp_f32_e32 v107, v94
	v_exp_f32_e32 v92, v111
	v_cvt_pk_bf16_f32 v86, v89, v90
	v_cvt_pk_bf16_f32 v88, v236, v206
	v_add_f32_e32 v109, v107, v91
	v_pk_add_f32 v[80:81], v[108:109], v[92:93]
	v_cvt_pk_bf16_f32 v87, v91, v92
	v_add_f32_e32 v80, v80, v81
	v_cvt_pk_bf16_f32 v81, v207, v96
	v_cvt_pk_bf16_f32 v89, v237, v234
	v_cvt_pk_bf16_f32 v90, v235, v98
	v_cvt_pk_bf16_f32 v91, v99, v100
	v_cvt_pk_bf16_f32 v92, v101, v102
	v_cvt_pk_bf16_f32 v93, v103, v104
	v_cvt_pk_bf16_f32 v94, v105, v106
	v_cvt_pk_bf16_f32 v95, v107, v108
	ds_read_b64_tr_b16 v[96:97], v226 offset:34944
	ds_read_b64_tr_b16 v[98:99], v226 offset:37504
	ds_read_b64_tr_b16 v[100:101], v226 offset:40064
	ds_read_b64_tr_b16 v[102:103], v226 offset:42624
	ds_read_b64_tr_b16 v[104:105], v226 offset:45184
	ds_read_b64_tr_b16 v[106:107], v226 offset:47744
	ds_read_b64_tr_b16 v[108:109], v226 offset:50304
	ds_read_b64_tr_b16 v[110:111], v226 offset:52864
	ds_read_b64_tr_b16 v[234:235], v226 offset:35008
	ds_read_b64_tr_b16 v[236:237], v226 offset:37568
	ds_read_b64_tr_b16 v[238:239], v226 offset:40128
	ds_read_b64_tr_b16 v[240:241], v226 offset:42688
	ds_read_b64_tr_b16 v[242:243], v226 offset:45248
	ds_read_b64_tr_b16 v[244:245], v226 offset:47808
	ds_read_b64_tr_b16 v[246:247], v226 offset:50368
	ds_read_b64_tr_b16 v[248:249], v226 offset:52928
	v_add_f32_e32 v203, v203, v80
	v_cvt_pk_bf16_f32 v80, v199, v0
	s_nop 1
	s_waitcnt lgkmcnt(15)
	v_mfma_f32_32x32x16_bf16 v[64:79], v[148:151], v[80:83], v[64:79]
	v_mfma_f32_32x32x16_bf16 v[48:63], v[156:159], v[80:83], v[48:63]
	v_mfma_f32_32x32x16_bf16 v[64:79], v[152:155], v[84:87], v[64:79]
	v_mfma_f32_32x32x16_bf16 v[48:63], v[160:163], v[84:87], v[48:63]
	v_mfma_f32_32x32x16_bf16 v[64:79], v[164:167], v[88:91], v[64:79]
	v_mfma_f32_32x32x16_bf16 v[48:63], v[172:175], v[88:91], v[48:63]
	v_mfma_f32_32x32x16_bf16 v[64:79], v[168:171], v[92:95], v[64:79]
	v_mfma_f32_32x32x16_bf16 v[48:63], v[176:179], v[92:95], v[48:63]
	s_waitcnt lgkmcnt(14)
	v_mfma_f32_32x32x16_bf16 v[32:47], v[96:99], v[80:83], v[32:47]
	s_waitcnt lgkmcnt(6)
	v_mfma_f32_32x32x16_bf16 v[16:31], v[234:237], v[80:83], v[16:31]
	v_mfma_f32_32x32x16_bf16 v[32:47], v[100:103], v[84:87], v[32:47]
	s_waitcnt lgkmcnt(4)
	v_mfma_f32_32x32x16_bf16 v[16:31], v[238:241], v[84:87], v[16:31]
	v_mfma_f32_32x32x16_bf16 v[32:47], v[104:107], v[88:91], v[32:47]
	s_waitcnt lgkmcnt(2)
	v_mfma_f32_32x32x16_bf16 v[16:31], v[242:245], v[88:91], v[16:31]
	v_mfma_f32_32x32x16_bf16 v[32:47], v[108:111], v[92:95], v[32:47]
	s_waitcnt lgkmcnt(0)
	v_mfma_f32_32x32x16_bf16 v[16:31], v[246:249], v[92:95], v[16:31]
	s_branch .Law_w0done

; __device__ __forceinline__ float fast_exp2(float x) { return __builtin_amdgcn_exp2f(x); }
; #define MFMA32(a, b, c) __builtin_amdgcn_mfma_f32_32x32x16_bf16((a), (b), (c), 0, 0, 0)
; template <bool DIFF, int NDV>
; __device__ __forceinline__ void attn_tile(f32x16 (&o)[NDV], float& l, const bf16x8 (&qf)[4], const float sref, LAS const char* kc, LAS const char* vc,
;                                           bool masked, int kb0, int qrow) {
;     ...
;     float rs = 0.f;
; #pragma unroll
;     for (int i = 0; i < 16; ++i) { s0[i] = fast_exp2(s0[i]); s1[i] = fast_exp2(s1[i]); rs += s0[i] + s1[i]; }
;     l += rs;
;     bf16x8 pb[4];
;     pb[0] = pack8(s0, 0); pb[1] = pack8(s0, 1); pb[2] = pack8(s1, 0); pb[3] = pack8(s1, 1);
;     if (NDV == 4) {
;         bf16x8 vf2[8];
; #pragma unroll
;         for (int d = 0; d < 2; ++d)
; #pragma unroll
;             for (int kk = 0; kk < 4; ++kk) vf2[d * 4 + kk] = vtr8(vc + kk * 16 * ATT_VP + (d + 2) * 64, 8 * ATT_VP);
;         __builtin_amdgcn_sched_barrier(0);
; #pragma unroll
;         for (int kk = 0; kk < 4; ++kk) { o[0] = MFMA32(vf[kk], pb[kk], o[0]); o[1] = MFMA32(vf[4 + kk], pb[kk], o[1]); }
; #pragma unroll
;         for (int kk = 0; kk < 4; ++kk) { o[2] = MFMA32(vf2[kk], pb[kk], o[2]); o[NDV - 1] = MFMA32(vf2[4 + kk], pb[kk], o[NDV - 1]); }
.Law_nw1:
	v_exp_f32_e32 v199, v96
	s_nop 7
	v_exp_f32_e32 v236, v80
	v_exp_f32_e32 v0, v97
	v_exp_f32_e32 v14, v81
	v_exp_f32_e32 v237, v82
	v_add_f32_e32 v15, v236, v199
	v_exp_f32_e32 v234, v83
	v_pk_add_f32 v[80:81], v[14:15], v[0:1]
	v_exp_f32_e32 v15, v98
	v_pk_add_f32 v[96:97], v[80:81], v[80:81] op_sel_hi:[0,1]
	v_exp_f32_e32 v96, v99
	v_exp_f32_e32 v98, v85
	v_add_f32_e32 v235, v237, v15
	v_pk_add_f32 v[80:81], v[234:235], v[96:97]
	s_nop 0
	v_pk_add_f32 v[82:83], v[80:81], v[80:81] op_sel_hi:[0,1]
	v_exp_f32_e32 v97, v100
	v_exp_f32_e32 v235, v84
	v_exp_f32_e32 v82, v101
	v_exp_f32_e32 v100, v87
	v_add_f32_e32 v99, v235, v97
	v_pk_add_f32 v[80:81], v[98:99], v[82:83]
	v_exp_f32_e32 v83, v102
	v_pk_add_f32 v[84:85], v[80:81], v[80:81] op_sel_hi:[0,1]
	v_exp_f32_e32 v99, v86
	v_exp_f32_e32 v84, v103
	v_exp_f32_e32 v102, v89
	v_cvt_pk_bf16_f32 v82, v97, v82
	v_add_f32_e32 v101, v99, v83
	v_pk_add_f32 v[80:81], v[100:101], v[84:85]
	v_exp_f32_e32 v85, v104
	v_pk_add_f32 v[86:87], v[80:81], v[80:81] op_sel_hi:[0,1]
	v_exp_f32_e32 v101, v88
	v_exp_f32_e32 v86, v105
	v_exp_f32_e32 v104, v91
	v_cvt_pk_bf16_f32 v83, v83, v84
	v_add_f32_e32 v103, v101, v85
	v_pk_add_f32 v[80:81], v[102:103], v[86:87]
	v_exp_f32_e32 v87, v106
	v_pk_add_f32 v[88:89], v[80:81], v[80:81] op_sel_hi:[0,1]
	v_exp_f32_e32 v103, v90
	v_exp_f32_e32 v88, v107
	v_exp_f32_e32 v106, v93
	v_cvt_pk_bf16_f32 v84, v85, v86
	v_add_f32_e32 v105, v103, v87
	v_pk_add_f32 v[80:81], v[104:105], v[88:89]
	v_exp_f32_e32 v89, v108
	v_pk_add_f32 v[90:91], v[80:81], v[80:81] op_sel_hi:[0,1]
	v_exp_f32_e32 v105, v92
	v_exp_f32_e32 v90, v109
	v_exp_f32_e32 v108, v95
	v_cvt_pk_bf16_f32 v85, v87, v88
	v_add_f32_e32 v107, v105, v89
	v_pk_add_f32 v[80:81], v[106:107], v[90:91]
	v_exp_f32_e32 v91, v110
	v_pk_add_f32 v[92:93], v[80:81], v[80:81] op_sel_hi:[0,1]
	v_exp_f32_e32 v107, v94
	v_exp_f32_e32 v92, v111
	v_cvt_pk_bf16_f32 v86, v89, v90
	v_cvt_pk_bf16_f32 v88, v236, v14
	v_add_f32_e32 v109, v107, v91
	v_pk_add_f32 v[80:81], v[108:109], v[92:93]
	v_cvt_pk_bf16_f32 v87, v91, v92
	v_add_f32_e32 v80, v80, v81
	v_cvt_pk_bf16_f32 v81, v15, v96
	v_cvt_pk_bf16_f32 v89, v237, v234
	v_cvt_pk_bf16_f32 v90, v235, v98
	v_cvt_pk_bf16_f32 v91, v99, v100
	v_cvt_pk_bf16_f32 v92, v101, v102
	v_cvt_pk_bf16_f32 v93, v103, v104
	v_cvt_pk_bf16_f32 v94, v105, v106
	v_cvt_pk_bf16_f32 v95, v107, v108
	ds_read_b64_tr_b16 v[96:97], v226 offset:55424
	ds_read_b64_tr_b16 v[98:99], v226 offset:57984
	ds_read_b64_tr_b16 v[100:101], v226 offset:60544
	ds_read_b64_tr_b16 v[102:103], v226 offset:63104
	ds_read_b64_tr_b16 v[104:105], v227 offset:30848
	ds_read_b64_tr_b16 v[106:107], v227 offset:33408
	ds_read_b64_tr_b16 v[108:109], v227 offset:35968
	ds_read_b64_tr_b16 v[110:111], v227 offset:38528
	ds_read_b64_tr_b16 v[234:235], v226 offset:55488
	ds_read_b64_tr_b16 v[236:237], v226 offset:58048
	ds_read_b64_tr_b16 v[238:239], v226 offset:60608
	ds_read_b64_tr_b16 v[240:241], v226 offset:63168
	ds_read_b64_tr_b16 v[242:243], v227 offset:30912
	ds_read_b64_tr_b16 v[244:245], v227 offset:33472
	ds_read_b64_tr_b16 v[246:247], v227 offset:36032
	ds_read_b64_tr_b16 v[248:249], v227 offset:38592
	v_add_f32_e32 v203, v203, v80
	v_cvt_pk_bf16_f32 v80, v199, v0
	s_nop 1
	s_waitcnt lgkmcnt(15)
	v_mfma_f32_32x32x16_bf16 v[64:79], v[152:155], v[80:83], v[64:79]
	v_mfma_f32_32x32x16_bf16 v[48:63], v[164:167], v[80:83], v[48:63]
	v_mfma_f32_32x32x16_bf16 v[64:79], v[160:163], v[84:87], v[64:79]
	v_mfma_f32_32x32x16_bf16 v[48:63], v[168:171], v[84:87], v[48:63]
	v_mfma_f32_32x32x16_bf16 v[64:79], v[172:175], v[88:91], v[64:79]
	v_mfma_f32_32x32x16_bf16 v[48:63], v[176:179], v[88:91], v[48:63]
	v_mfma_f32_32x32x16_bf16 v[64:79], v[156:159], v[92:95], v[64:79]
	v_mfma_f32_32x32x16_bf16 v[48:63], v[148:151], v[92:95], v[48:63]
	s_waitcnt lgkmcnt(14)
	v_mfma_f32_32x32x16_bf16 v[32:47], v[96:99], v[80:83], v[32:47]
	s_waitcnt lgkmcnt(6)
	v_mfma_f32_32x32x16_bf16 v[16:31], v[234:237], v[80:83], v[16:31]
	v_mfma_f32_32x32x16_bf16 v[32:47], v[100:103], v[84:87], v[32:47]
	s_waitcnt lgkmcnt(4)
	v_mfma_f32_32x32x16_bf16 v[16:31], v[238:241], v[84:87], v[16:31]
	v_mfma_f32_32x32x16_bf16 v[32:47], v[104:107], v[88:91], v[32:47]
	s_waitcnt lgkmcnt(2)
	v_mfma_f32_32x32x16_bf16 v[16:31], v[242:245], v[88:91], v[16:31]
	v_mfma_f32_32x32x16_bf16 v[32:47], v[108:111], v[92:95], v[32:47]
	s_waitcnt lgkmcnt(0)
	v_mfma_f32_32x32x16_bf16 v[16:31], v[246:249], v[92:95], v[16:31]
	s_cmp_ge_u32 s37, s39
	s_cselect_b64 s[10:11], -1, 0
	s_branch .LBB0_42
